# LDS-DMA also for the attention k_pe tile (swizzle on source address), k_pe ds_write removed; only the 2 V writes remain in the inter-barrier segment
# speedup vs baseline: 1.0042x; 1.0008x over previous
.LBB0_560:
	s_ashr_i32 s0, s4, 3
	s_and_b32 s14, s4, 7
	s_ashr_i32 s1, s0, 31
	s_lshl_b32 s4, s5, 8
	s_lshl_b64 s[46:47], s[0:1], 12
	s_and_b32 s4, s4, 0xf00
	s_or_b32 s46, s46, s4
	s_mul_i32 s4, s47, 0xc00
	s_mul_hi_u32 s5, s46, 0xc00
	s_add_i32 s5, s5, s4
	s_mul_i32 s4, s46, 0xc00
	s_add_u32 s6, s48, s4
	s_addc_u32 s7, s49, s5
	s_lshl_b32 s13, s14, 7
	s_lshl_b32 s4, s14, 8
	s_add_u32 s4, s6, s4
	s_addc_u32 s5, s7, 0
	s_barrier
	s_add_u32 s6, s6, s13
	v_mbcnt_lo_u32_b32 v60, -1, 0
	v_mbcnt_hi_u32_b32 v60, -1, v60
	s_addc_u32 s7, s7, 0
	v_or_b32_e32 v34, s33, v60
	v_ashrrev_i32_e32 v61, 1, v34
	s_movk_i32 s15, 0xffe0
	v_bfe_u32 v176, v60, 5, 1
	v_bfi_b32 v48, s15, v61, v60
	v_mov_b64_e32 v[0:1], s[6:7]
	v_lshlrev_b32_e32 v160, 4, v176
	v_mad_i64_i32 v[0:1], s[6:7], v48, s91, v[0:1]
	v_lshl_add_u64 v[12:13], v[0:1], 0, v[160:161]
	global_load_dwordx4 v[0:3], v[12:13], off offset:2048
	global_load_dwordx4 v[4:7], v[12:13], off offset:2080
	global_load_dwordx4 v[8:11], v[12:13], off offset:2112
	s_nop 0
	global_load_dwordx4 v[12:15], v[12:13], off offset:2144
	s_lshl_b64 s[6:7], s[0:1], 24
	s_add_u32 s16, s50, s6
	v_ashrrev_i32_e32 v36, 4, v34
	s_addc_u32 s17, s51, s7
	s_lshl_b32 s15, s14, 9
	v_add_u32_e32 v40, 32, v36
	s_add_u32 s16, s16, s15
	v_lshlrev_b32_e32 v49, 3, v34
	v_ashrrev_i32_e32 v37, 31, v36
	v_ashrrev_i32_e32 v41, 31, v40
	s_addc_u32 s17, s17, 0
	v_and_b32_e32 v16, 0x78, v49
	v_lshlrev_b64 v[52:53], 12, v[36:37]
	v_lshlrev_b64 v[20:21], 12, v[40:41]
	s_lshl_b64 s[0:1], s[0:1], 19
	v_ashrrev_i32_e32 v42, 3, v34
	v_lshlrev_b32_e32 v38, 1, v16
	v_lshl_add_u64 v[16:17], s[16:17], 0, v[52:53]
	v_lshl_add_u64 v[20:21], s[16:17], 0, v[20:21]
	s_add_u32 s16, s8, s0
	v_ashrrev_i32_e32 v43, 31, v42
	s_addc_u32 s17, s9, s1
	v_lshlrev_b64 v[54:55], 7, v[42:43]
	v_lshlrev_b32_e32 v34, 4, v34
	v_mov_b32_e32 v39, v161
	v_lshl_add_u64 v[32:33], s[16:17], 0, v[54:55]
	v_and_b32_e32 v44, 0x70, v34
	v_mov_b32_e32 v45, v161
	v_lshl_add_u64 v[56:57], v[16:17], 0, v[38:39]
	v_lshl_add_u64 v[28:29], v[20:21], 0, v[38:39]
	v_lshl_add_u64 v[58:59], v[32:33], 0, v[44:45]
	global_load_dwordx4 v[16:19], v[56:57], off offset:256
	global_load_dwordx4 v[24:27], v[56:57], off
	global_load_dwordx4 v[20:23], v[28:29], off offset:256
	global_load_dwordx4 v[32:35], v[58:59], off
	v_mov_b64_e32 v[46:47], s[4:5]
	global_load_dwordx4 v[28:31], v[28:29], off
	v_mad_i64_i32 v[46:47], s[4:5], v48, s91, v[46:47]
	v_lshl_add_u64 v[46:47], v[46:47], 0, v[160:161]
	global_load_dwordx4 v[120:123], v[46:47], off
	global_load_dwordx4 v[124:127], v[46:47], off offset:32
	global_load_dwordx4 v[116:119], v[46:47], off offset:64
	global_load_dwordx4 v[112:115], v[46:47], off offset:96
	global_load_dwordx4 v[108:111], v[46:47], off offset:128
	global_load_dwordx4 v[104:107], v[46:47], off offset:160
	global_load_dwordx4 v[100:103], v[46:47], off offset:192
	global_load_dwordx4 v[96:99], v[46:47], off offset:224
	v_lshlrev_b32_e32 v63, 4, v60
	s_add_i32 s5, 0, 0x14800
	v_and_b32_e32 v64, 0x70, v63
	v_and_b32_e32 v240, 0xf0, v63
	v_lshlrev_b32_e32 v241, 3, v60
	v_and_b32_e32 v241, 0x70, v241
	v_lshrrev_b32_e32 v242, 1, v60
	v_bitop3_b32 v37, v176, v242, 7 bitop3:0x78
	v_lshl_add_u32 v65, v48, 7, s5
	v_bitop3_b32 v39, v160, v241, 32 bitop3:0x36
	v_lshl_add_u32 v37, v37, 4, v65
	v_add_u32_e32 v184, v65, v39
	s_movk_i32 s5, 0x60
	v_mov_b32_e32 v62, s33
	s_movk_i32 s14, 0x70
	s_add_i32 s4, 0, 0x14000
	s_cmp_lg_u32 0, -1
	v_and_b32_e32 v177, 31, v60
	s_cselect_b32 s16, 0, 0
	v_or_b32_e32 v66, 64, v160
	v_or_b32_e32 v67, 0x60, v160
	s_waitcnt vmcnt(16)
	ds_write_b128 v37, v[0:3]
	s_waitcnt vmcnt(15)
	ds_write_b128 v184, v[4:7]
	v_bitop3_b32 v0, v160, v241, 64 bitop3:0x36
	v_add_u32_e32 v183, v65, v0
	v_bitop3_b32 v0, v160, v241, s5 bitop3:0x36
	v_add_u32_e32 v182, v65, v0
	v_and_b32_e32 v0, 0xfffff0, v36
	v_lshlrev_b32_e32 v1, 1, v36
	v_and_b32_e32 v4, 0xfffff0, v40
	v_lshlrev_b32_e32 v5, 1, v40
	v_and_or_b32 v0, v1, 8, v0
	v_and_or_b32 v4, v5, 8, v4
	v_lshrrev_b32_e32 v1, 1, v36
	v_lshrrev_b32_e32 v0, 1, v0
	v_bfe_u32 v2, v49, 5, 2
	v_and_b32_e32 v3, 3, v36
	v_lshrrev_b32_e32 v4, 1, v4
	v_or_b32_e32 v0, v0, v2
	v_and_or_b32 v1, v1, 4, v3
	v_or_b32_e32 v2, v4, v2
	v_lshlrev_b32_e32 v0, 9, v0
	v_lshlrev_b32_e32 v1, 6, v1
	v_and_b32_e32 v3, 48, v38
	v_lshlrev_b32_e32 v2, 9, v2
	v_or3_b32 v0, v0, v1, v3
	v_or3_b32 v1, v2, v1, v3
	v_add_u32_e32 v185, 0, v0
	v_add_u32_e32 v186, 0, v1
	v_lshlrev_b32_e32 v0, 8, v36
	v_bitop3_b32 v1, v60, s14, v62 bitop3:0xc8
	v_or_b32_e32 v243, s33, v60
	v_and_b32_e32 v243, 0xf0, v243
	v_bitop3_b32 v0, v38, v0, v243 bitop3:0xde
	v_add_u32_e32 v187, 0, v0
	v_lshlrev_b32_e32 v0, 8, v40
	v_bitop3_b32 v0, v38, v0, v243 bitop3:0xde
	v_lshlrev_b32_e32 v1, 3, v42
	v_add_u32_e32 v188, 0, v0
	v_lshlrev_b32_e32 v0, 7, v42
	v_and_b32_e32 v1, 0x70, v1
	v_mov_b32_e32 v242, v1
	v_bitop3_b32 v75, v44, v0, v1 bitop3:0xde
	s_add_i32 s5, 0, 0x10000
	s_waitcnt vmcnt(14)
	ds_write_b128 v183, v[8:11]
	s_waitcnt vmcnt(13)
	ds_write_b128 v182, v[12:15]
	v_add_u32_e32 v0, s5, v75
	v_lshlrev_b32_e32 v8, 8, v177
	s_waitcnt vmcnt(0)
	s_waitcnt vmcnt(12)
	ds_write_b128 v185, v[16:19]
	s_waitcnt vmcnt(10)
	ds_write_b128 v186, v[20:23]
	ds_write_b128 v187, v[24:27] offset:32768
	s_waitcnt vmcnt(8)
	ds_write_b128 v188, v[28:31] offset:32768
	ds_write_b128 v0, v[32:35]
	v_bitop3_b32 v0, v160, v8, v240 bitop3:0xde
	v_add_u32_e32 v189, 0, v0
	s_waitcnt lgkmcnt(0)
	s_barrier
	ds_read_b128 v[0:3], v189 offset:32768
	ds_read_b128 v[48:51], v182
	v_or_b32_e32 v12, 32, v160
	v_bitop3_b32 v4, v12, v8, v240 bitop3:0xde
	v_add_u32_e32 v190, 0, v4
	s_waitcnt vmcnt(7) lgkmcnt(1)
	v_mfma_f32_32x32x16_bf16 v[32:47], v[0:3], v[120:123], 0
	ds_read_b128 v[0:3], v189 offset:40960
	ds_read_b128 v[4:7], v190 offset:32768
	v_lshlrev_b32_e32 v68, 7, v177
	v_bitop3_b32 v198, v160, v68, v241 bitop3:0xde
	v_add_u32_e32 v199, s5, v198
	v_bitop3_b32 v200, v12, v68, v241 bitop3:0xde
	v_add_u32_e32 v201, s5, v200
	s_waitcnt vmcnt(6) lgkmcnt(0)
	v_mfma_f32_32x32x16_bf16 v[32:47], v[4:7], v[124:127], v[32:47]
	v_bitop3_b32 v4, v66, v8, v240 bitop3:0xde
	v_add_u32_e32 v191, 0, v4
	ds_read_b128 v[4:7], v191 offset:32768
	v_bitop3_b32 v202, v66, v68, v241 bitop3:0xde
	v_add_u32_e32 v203, s5, v202
	v_and_b32_e32 v76, 63, v60
	v_and_b32_e32 v156, 0xffffffe0, v61
	v_mfma_f32_32x32x16_bf16 v[16:31], v[0:3], v[120:123], 0
	ds_read_b128 v[0:3], v190 offset:40960
	v_lshlrev_b32_e32 v61, 3, v76
	v_bitop3_b32 v204, v67, v68, v241 bitop3:0xde
	v_add_u32_e32 v205, s5, v204
	v_readlane_b32 s68, v254, 50
	v_readlane_b32 s69, v254, 51
	s_mov_b32 s5, s69
	s_waitcnt vmcnt(5) lgkmcnt(1)
	v_mfma_f32_32x32x16_bf16 v[32:47], v[4:7], v[116:119], v[32:47]
	v_bitop3_b32 v4, v67, v8, v240 bitop3:0xde
	v_add_u32_e32 v192, 0, v4
	ds_read_b128 v[4:7], v192 offset:32768
	v_readlane_b32 s70, v254, 52
	v_readlane_b32 s71, v254, 53
	v_readlane_b32 s72, v254, 54
	v_readlane_b32 s73, v254, 55
	s_waitcnt lgkmcnt(1)
	v_mfma_f32_32x32x16_bf16 v[16:31], v[0:3], v[124:127], v[16:31]
	ds_read_b128 v[0:3], v191 offset:40960
	v_readlane_b32 s74, v254, 56
	v_readlane_b32 s75, v254, 57
	v_readlane_b32 s76, v254, 58
	v_readlane_b32 s77, v254, 59
	v_readlane_b32 s78, v254, 60
	v_readlane_b32 s79, v254, 61
	s_waitcnt vmcnt(4) lgkmcnt(1)
	v_mfma_f32_32x32x16_bf16 v[32:47], v[4:7], v[112:115], v[32:47]
	v_or_b32_e32 v4, 0x80, v160
	v_bitop3_b32 v4, v4, v8, v240 bitop3:0xde
	v_add_u32_e32 v193, 0, v4
	ds_read_b128 v[4:7], v193 offset:32768
	v_readlane_b32 s80, v254, 62
	v_readlane_b32 s81, v254, 63
	v_readlane_b32 s82, v255, 0
	s_waitcnt lgkmcnt(1)
	v_mfma_f32_32x32x16_bf16 v[16:31], v[0:3], v[116:119], v[16:31]
	ds_read_b128 v[0:3], v192 offset:40960
	v_readlane_b32 s83, v255, 1
	v_add_co_u32_e32 v66, vcc, s89, v56
	v_mov_b32_e32 v78, 0xf149f2ca
	s_nop 0
	v_addc_co_u32_e32 v67, vcc, 0, v57, vcc
	s_waitcnt vmcnt(3) lgkmcnt(1)
	v_mfma_f32_32x32x16_bf16 v[32:47], v[4:7], v[108:111], v[32:47]
	v_or_b32_e32 v4, 0xa0, v160
	v_bitop3_b32 v4, v4, v8, v240 bitop3:0xde
	v_add_u32_e32 v194, 0, v4
	ds_read_b128 v[4:7], v194 offset:32768
	s_mov_b32 s68, s69
	s_mov_b32 s70, s69
	s_mov_b32 s71, s69
	s_waitcnt lgkmcnt(1)
	v_mfma_f32_32x32x16_bf16 v[16:31], v[0:3], v[112:115], v[16:31]
	ds_read_b128 v[0:3], v193 offset:40960
	s_mov_b32 s72, s69
	s_mov_b32 s73, s69
	s_mov_b32 s74, s69
	s_mov_b32 s75, s69
	s_mov_b32 s76, s69
	s_mov_b32 s77, s69
	s_waitcnt lgkmcnt(0)
	v_mfma_f32_32x32x16_bf16 v[16:31], v[0:3], v[108:111], v[16:31]
	ds_read_b128 v[0:3], v194 offset:40960
	s_mov_b32 s78, s69
	s_mov_b32 s79, s69
	s_mov_b32 s80, s69
	s_mov_b32 s81, s69
	s_mov_b32 s82, s69
	s_mov_b32 s83, s69
	s_waitcnt vmcnt(2)
	v_mfma_f32_32x32x16_bf16 v[32:47], v[4:7], v[104:107], v[32:47]
	v_or_b32_e32 v4, 0xc0, v160
	v_bitop3_b32 v4, v4, v8, v240 bitop3:0xde
	v_add_u32_e32 v195, 0, v4
	ds_read_b128 v[4:7], v195 offset:32768
	v_add_u32_e32 v207, 0, v75
	v_add_u32_e32 v208, 0x12000, v207
	v_lshl_add_u64 v[170:171], s[0:1], 0, v[54:55]
	s_waitcnt lgkmcnt(1)
	v_mfma_f32_32x32x16_bf16 v[16:31], v[0:3], v[104:107], v[16:31]
	ds_read_b128 v[0:3], v195 offset:40960
	v_mov_b32_e32 v179, 0
	s_waitcnt vmcnt(1) lgkmcnt(1)
	v_mfma_f32_32x32x16_bf16 v[32:47], v[4:7], v[100:103], v[32:47]
	v_or_b32_e32 v4, 0xe0, v160
	v_bitop3_b32 v4, v4, v8, v240 bitop3:0xde
	v_add_u32_e32 v196, 0, v4
	ds_read_b128 v[4:7], v196 offset:32768
	s_waitcnt lgkmcnt(1)
	v_mfma_f32_32x32x16_bf16 v[16:31], v[0:3], v[100:103], v[16:31]
	ds_read_b128 v[0:3], v196 offset:40960
	s_waitcnt vmcnt(0) lgkmcnt(1)
	v_mfma_f32_32x32x16_bf16 v[32:47], v[4:7], v[96:99], v[32:47]
	ds_read_b128 v[4:7], v199
	s_waitcnt lgkmcnt(1)
	v_mfma_f32_32x32x16_bf16 v[16:31], v[0:3], v[96:99], v[16:31]
	v_xor_b32_e32 v0, v160, v241
	v_add_u32_e32 v197, v65, v0
	ds_read_b128 v[0:3], v197
	ds_read_b128 v[8:11], v199 offset:4096
	s_mov_b32 s14, 0x3fffffc0
	v_bitop3_b32 v62, v60, s14, v62 bitop3:0xc8
	v_lshl_add_u32 v157, v62, 2, s4
	v_and_b32_e32 v62, 0xc0, v63
	s_waitcnt lgkmcnt(1)
	v_mfma_f32_32x32x16_bf16 v[32:47], v[4:7], v[0:3], v[32:47]
	s_mov_b32 s14, -1
	v_lshl_add_u32 v178, v177, 2, v157
	s_waitcnt lgkmcnt(0)
	v_mfma_f32_32x32x16_bf16 v[16:31], v[8:11], v[0:3], v[16:31]
	ds_read_b128 v[0:3], v201
	ds_read_b128 v[4:7], v184
	ds_read_b128 v[8:11], v201 offset:4096
	ds_read_b128 v[12:15], v183
	s_waitcnt lgkmcnt(2)
	v_mfma_f32_32x32x16_bf16 v[32:47], v[0:3], v[4:7], v[32:47]
	ds_read_b128 v[0:3], v203
	s_waitcnt lgkmcnt(2)
	v_mfma_f32_32x32x16_bf16 v[16:31], v[8:11], v[4:7], v[16:31]
	v_lshlrev_b32_e32 v5, 1, v60
	v_and_or_b32 v4, v61, 24, v62
	v_and_b32_e32 v5, 32, v5
	v_and_b32_e32 v6, 0x100, v61
	v_or3_b32 v61, v4, v5, v6
	ds_read_b128 v[4:7], v203 offset:4096
	ds_read_b128 v[62:65], v205 offset:4096
	s_waitcnt lgkmcnt(2)
	v_mfma_f32_32x32x16_bf16 v[32:47], v[0:3], v[12:15], v[32:47]
	ds_read_b128 v[0:3], v205
	v_add_u32_e32 v181, s16, v61
	v_writelane_b32 v254, s4, 50
	s_nop 1
	v_writelane_b32 v255, s18, 0
	v_writelane_b32 v254, s5, 51
	s_waitcnt lgkmcnt(2)
	v_mfma_f32_32x32x16_bf16 v[16:31], v[4:7], v[12:15], v[16:31]
	v_writelane_b32 v255, s19, 1
	s_mov_b64 s[4:5], 0x40000
	v_writelane_b32 v254, s6, 52
	v_writelane_b32 v254, s7, 53
	v_writelane_b32 v254, s8, 54
	v_writelane_b32 v254, s9, 55
	v_writelane_b32 v254, s10, 56
	s_waitcnt lgkmcnt(0)
	v_mfma_f32_32x32x16_bf16 v[32:47], v[0:3], v[48:51], v[32:47]
	v_writelane_b32 v254, s11, 57
	v_writelane_b32 v254, s12, 58
	v_writelane_b32 v254, s13, 59
	v_writelane_b32 v254, s14, 60
	v_writelane_b32 v254, s15, 61
	v_mov_b64_e32 v[0:1], s[68:69]
	v_lshl_add_u64 v[158:159], s[6:7], 0, v[52:53]
	v_mfma_f32_32x32x16_bf16 v[16:31], v[62:65], v[48:51], v[16:31]
	s_nop 3
	v_max_f32_e32 v48, v33, v33
	v_max_f32_e32 v49, v32, v32
	v_max_f32_e32 v48, v49, v48
	v_max3_f32 v74, v48, v34, v35
	v_lshl_add_u64 v[48:49], v[56:57], 0, s[4:5]
	s_mov_b64 s[4:5], 0x60000
	v_lshl_add_u64 v[62:63], v[56:57], 0, s[4:5]
	s_mov_b32 s4, 0x60000
	v_add_co_u32_e32 v56, vcc, s4, v56
	global_load_dwordx4 v[48:51], v[48:49], off offset:256
	s_nop 0
	global_load_dwordx4 v[62:65], v[62:63], off offset:256
	v_addc_co_u32_e32 v57, vcc, 0, v57, vcc
	global_load_dwordx4 v[66:69], v[66:67], off
	s_nop 0
	global_load_dwordx4 v[70:73], v[56:57], off
	v_add_co_u32_e32 v56, vcc, s63, v58
	v_max3_f32 v74, v74, v36, v37
	s_nop 0
	v_addc_co_u32_e32 v57, vcc, 0, v59, vcc
	global_load_dwordx4 v[56:59], v[56:57], off
	v_max3_f32 v74, v74, v38, v39
	v_max3_f32 v74, v74, v40, v41
	v_max3_f32 v74, v74, v42, v43
	v_max3_f32 v74, v74, v44, v45
	v_max3_f32 v74, v74, v46, v47
	v_max3_f32 v74, v74, v16, v17
	v_max3_f32 v74, v74, v18, v19
	v_max3_f32 v74, v74, v20, v21
	v_max3_f32 v74, v74, v22, v23
	v_max3_f32 v74, v74, v24, v25
	v_max3_f32 v74, v74, v26, v27
	v_max3_f32 v74, v74, v28, v29
	v_max3_f32 v74, v74, v30, v31
	v_mov_b32_e32 v77, v74
	s_nop 1
	v_permlane32_swap_b32_e32 v74, v77
	v_max_f32_e32 v77, v77, v77
	v_max_f32_e32 v74, v74, v74
	v_max_f32_e32 v74, v74, v77
	v_add_f32_e32 v77, 0x7149f2ca, v74
	v_max_f32_e32 v74, 0xf149f2ca, v74
	v_cmp_ge_f32_e32 vcc, s90, v77
	v_sub_f32_e32 v77, 0xf149f2ca, v74
	v_mul_f32_e32 v77, 0x3dd53b94, v77
	v_exp_f32_e32 v77, v77
	s_cmp_eq_u64 vcc, exec
	s_cselect_b64 vcc, -1, 0
	v_cndmask_b32_e32 v209, v74, v78, vcc
	v_mul_f32_e32 v74, 0xbdd53b94, v209
	v_cndmask_b32_e64 v206, v77, 1.0, vcc
	v_mov_b32_e32 v77, v74
	v_fmamk_f32 v32, v32, 0x3dd53b94, v74
	v_fmamk_f32 v33, v33, 0x3dd53b94, v74
	v_fmamk_f32 v34, v34, 0x3dd53b94, v74
	v_fmamk_f32 v35, v35, 0x3dd53b94, v74
	v_fmamk_f32 v36, v36, 0x3dd53b94, v74
	v_fmamk_f32 v37, v37, 0x3dd53b94, v74
	v_fmamk_f32 v38, v38, 0x3dd53b94, v74
	v_fmamk_f32 v39, v39, 0x3dd53b94, v74
	v_fmamk_f32 v40, v40, 0x3dd53b94, v74
	v_fmamk_f32 v41, v41, 0x3dd53b94, v74
	v_fmamk_f32 v42, v42, 0x3dd53b94, v74
	v_fmamk_f32 v43, v43, 0x3dd53b94, v74
	v_fmamk_f32 v44, v44, 0x3dd53b94, v74
	v_fmamk_f32 v45, v45, 0x3dd53b94, v74
	v_fmamk_f32 v46, v46, 0x3dd53b94, v74
	v_fmac_f32_e32 v77, 0x3dd53b94, v47
	v_pk_fma_f32 v[140:141], v[16:17], s[60:61], v[74:75] op_sel_hi:[1,0,0]
	v_bitop3_b32 v16, v60, 15, s33 bitop3:0xc8
	v_exp_f32_e32 v175, v32
	v_exp_f32_e32 v217, v33
	v_exp_f32_e32 v149, v34
	v_exp_f32_e32 v216, v35
	v_exp_f32_e32 v150, v36
	v_exp_f32_e32 v174, v37
	v_exp_f32_e32 v151, v38
	v_exp_f32_e32 v173, v39
	v_exp_f32_e32 v154, v40
	v_exp_f32_e32 v172, v41
	v_exp_f32_e32 v153, v42
	v_exp_f32_e32 v155, v43
	v_exp_f32_e32 v145, v44
	v_exp_f32_e32 v147, v45
	v_exp_f32_e32 v144, v46
	v_exp_f32_e32 v146, v77
	v_lshlrev_b32_e32 v16, 4, v16
	v_writelane_b32 v254, s16, 62
	v_mov_b64_e32 v[14:15], s[82:83]
	s_waitcnt vmcnt(0)
	s_addk_i32 s16, 0x4000
	v_or3_b32 v158, v158, s15, v16
	v_bitop3_b32 v16, v60, 7, s33 bitop3:0xc8
	v_mov_b64_e32 v[2:3], s[70:71]
	v_mov_b64_e32 v[4:5], s[72:73]
	v_mov_b64_e32 v[6:7], s[74:75]
	v_mov_b64_e32 v[8:9], s[76:77]
	v_mov_b64_e32 v[10:11], s[78:79]
	v_mov_b64_e32 v[12:13], s[80:81]
	v_pk_fma_f32 v[134:135], v[30:31], s[60:61], v[74:75] op_sel_hi:[1,0,0]
	v_pk_fma_f32 v[136:137], v[28:29], s[60:61], v[74:75] op_sel_hi:[1,0,0]
	v_pk_fma_f32 v[142:143], v[26:27], s[60:61], v[74:75] op_sel_hi:[1,0,0]
	v_pk_fma_f32 v[128:129], v[24:25], s[60:61], v[74:75] op_sel_hi:[1,0,0]
	v_pk_fma_f32 v[130:131], v[22:23], s[60:61], v[74:75] op_sel_hi:[1,0,0]
	v_pk_fma_f32 v[132:133], v[20:21], s[60:61], v[74:75] op_sel_hi:[1,0,0]
	v_pk_fma_f32 v[138:139], v[18:19], s[60:61], v[74:75] op_sel_hi:[1,0,0]
	s_waitcnt vmcnt(4)
	ds_write_b128 v185, v[48:51] offset:16384
	s_waitcnt vmcnt(3)
	ds_write_b128 v186, v[62:65] offset:16384
	s_waitcnt vmcnt(2)
	ds_write_b128 v187, v[66:69] offset:49152
	s_waitcnt vmcnt(1)
	ds_write_b128 v188, v[70:73] offset:49152
	s_waitcnt vmcnt(0)
	ds_write_b128 v208, v[56:59]
	v_add_u32_e32 v180, s16, v61
	v_lshl_or_b32 v170, v16, 4, v170
	v_mov_b64_e32 v[62:63], v[14:15]
	v_mov_b64_e32 v[46:47], v[14:15]
	v_mov_b64_e32 v[30:31], v[14:15]
	v_writelane_b32 v254, s17, 63
	v_cmp_gt_u32_e64 s[4:5], 32, v76
	v_mov_b64_e32 v[60:61], v[12:13]
	v_mov_b64_e32 v[58:59], v[10:11]
	v_mov_b64_e32 v[56:57], v[8:9]
	v_mov_b64_e32 v[54:55], v[6:7]
	v_mov_b64_e32 v[52:53], v[4:5]
	v_mov_b64_e32 v[50:51], v[2:3]
	v_mov_b64_e32 v[48:49], v[0:1]
	v_mov_b64_e32 v[44:45], v[12:13]
	v_mov_b64_e32 v[42:43], v[10:11]
	v_mov_b64_e32 v[40:41], v[8:9]
	v_mov_b64_e32 v[38:39], v[6:7]
	v_mov_b64_e32 v[36:37], v[4:5]
	v_mov_b64_e32 v[34:35], v[2:3]
	v_mov_b64_e32 v[32:33], v[0:1]
	v_mov_b64_e32 v[28:29], v[12:13]
	v_mov_b64_e32 v[26:27], v[10:11]
	v_mov_b64_e32 v[24:25], v[8:9]
	v_mov_b64_e32 v[22:23], v[6:7]
	v_mov_b64_e32 v[20:21], v[4:5]
	v_mov_b64_e32 v[18:19], v[2:3]
	v_mov_b64_e32 v[16:17], v[0:1]
	s_waitcnt lgkmcnt(0)
	s_barrier
.LBB0_561:
	ds_read_b128 v[64:67], v189 offset:49152
	ds_read_b128 v[68:71], v189 offset:57344
	ds_read_b128 v[210:213], v190 offset:49152
	ds_read_b128 v[218:221], v190 offset:57344
	s_add_i32 s0, 0, 0x12000
	v_add_f32_e32 v148, 0, v175
	s_waitcnt lgkmcnt(3)
	v_mfma_f32_32x32x16_bf16 v[80:95], v[64:67], v[120:123], 0
	v_add_f32_e32 v148, v217, v148
	v_add_f32_e32 v148, v149, v148
	v_add_f32_e32 v148, v216, v148
	v_add_f32_e32 v148, v150, v148
	v_add_f32_e32 v148, v174, v148
	v_add_f32_e32 v148, v151, v148
	v_add_f32_e32 v148, v173, v148
	s_waitcnt lgkmcnt(2)
	v_mfma_f32_32x32x16_bf16 v[64:79], v[68:71], v[120:123], 0
	v_add_f32_e32 v148, v154, v148
	v_add_f32_e32 v148, v172, v148
	v_add_f32_e32 v148, v153, v148
	v_add_f32_e32 v148, v155, v148
	v_exp_f32_e32 v140, v140
	v_add_f32_e32 v148, v145, v148
	v_exp_f32_e32 v141, v141
	s_waitcnt lgkmcnt(1)
	v_mfma_f32_32x32x16_bf16 v[80:95], v[210:213], v[124:127], v[80:95]
	v_add_f32_e32 v148, v147, v148
	v_exp_f32_e32 v138, v138
	v_add_f32_e32 v148, v144, v148
	v_exp_f32_e32 v139, v139
	v_add_f32_e32 v148, v146, v148
	v_exp_f32_e32 v132, v132
	v_add_f32_e32 v148, v140, v148
	s_waitcnt lgkmcnt(0)
	v_mfma_f32_32x32x16_bf16 v[64:79], v[218:221], v[124:127], v[64:79]
	ds_read_b128 v[210:213], v191 offset:49152
	ds_read_b128 v[218:221], v191 offset:57344
	v_exp_f32_e32 v133, v133
	v_add_f32_e32 v148, v141, v148
	v_exp_f32_e32 v130, v130
	v_add_f32_e32 v148, v138, v148
	v_exp_f32_e32 v131, v131
	v_add_f32_e32 v148, v139, v148
	s_waitcnt lgkmcnt(1)
	v_mfma_f32_32x32x16_bf16 v[80:95], v[210:213], v[116:119], v[80:95]
	v_exp_f32_e32 v128, v128
	v_add_f32_e32 v148, v132, v148
	v_exp_f32_e32 v129, v129
	v_add_f32_e32 v148, v133, v148
	v_exp_f32_e32 v142, v142
	v_add_f32_e32 v148, v130, v148
	v_exp_f32_e32 v143, v143
	s_waitcnt lgkmcnt(0)
	v_mfma_f32_32x32x16_bf16 v[64:79], v[218:221], v[116:119], v[64:79]
	ds_read_b128 v[210:213], v192 offset:49152
	ds_read_b128 v[218:221], v192 offset:57344
	v_add_f32_e32 v148, v131, v148
	v_exp_f32_e32 v136, v136
	v_add_f32_e32 v148, v128, v148
	v_exp_f32_e32 v137, v137
	v_add_f32_e32 v148, v129, v148
	v_exp_f32_e32 v134, v134
	s_waitcnt lgkmcnt(1)
	v_mfma_f32_32x32x16_bf16 v[80:95], v[210:213], v[112:115], v[80:95]
	v_add_f32_e32 v148, v142, v148
	v_exp_f32_e32 v135, v135
	v_add_f32_e32 v148, v143, v148
	v_add_f32_e32 v148, v136, v148
	v_add_f32_e32 v148, v137, v148
	v_add_f32_e32 v148, v134, v148
	s_waitcnt lgkmcnt(0)
	v_mfma_f32_32x32x16_bf16 v[64:79], v[218:221], v[112:115], v[64:79]
	ds_read_b128 v[210:213], v193 offset:49152
	ds_read_b128 v[218:221], v193 offset:57344
	ds_read_b128 v[232:235], v194 offset:49152
	ds_read_b128 v[236:239], v194 offset:57344
	s_waitcnt lgkmcnt(3)
	v_mfma_f32_32x32x16_bf16 v[80:95], v[210:213], v[108:111], v[80:95]
	s_waitcnt lgkmcnt(2)
	v_mfma_f32_32x32x16_bf16 v[64:79], v[218:221], v[108:111], v[64:79]
	ds_read_b128 v[210:213], v195 offset:49152
	ds_read_b128 v[218:221], v195 offset:57344
	s_waitcnt lgkmcnt(3)
	v_mfma_f32_32x32x16_bf16 v[80:95], v[232:235], v[104:107], v[80:95]
	s_waitcnt lgkmcnt(2)
	v_mfma_f32_32x32x16_bf16 v[64:79], v[236:239], v[104:107], v[64:79]
	ds_read_b128 v[232:235], v196 offset:49152
	ds_read_b128 v[236:239], v196 offset:57344
	s_waitcnt lgkmcnt(3)
	v_mfma_f32_32x32x16_bf16 v[80:95], v[210:213], v[100:103], v[80:95]
	v_add_u32_e32 v230, s0, v198
	v_add_u32_e32 v231, s0, v200
	s_waitcnt lgkmcnt(2)
	v_mfma_f32_32x32x16_bf16 v[64:79], v[218:221], v[100:103], v[64:79]
	ds_read_b128 v[210:213], v230
	ds_read_b128 v[218:221], v230 offset:4096
	ds_read_b128 v[222:225], v197
	s_waitcnt lgkmcnt(4)
	v_mfma_f32_32x32x16_bf16 v[80:95], v[232:235], v[96:99], v[80:95]
	s_waitcnt lgkmcnt(3)
	v_mfma_f32_32x32x16_bf16 v[64:79], v[236:239], v[96:99], v[64:79]
	ds_read_b128 v[232:235], v231
	ds_read_b128 v[236:239], v231 offset:4096
	ds_read_b128 v[226:229], v184
	s_waitcnt lgkmcnt(3)
	v_mfma_f32_32x32x16_bf16 v[80:95], v[210:213], v[222:225], v[80:95]
	v_mfma_f32_32x32x16_bf16 v[64:79], v[218:221], v[222:225], v[64:79]
	v_add_u32_e32 v244, s0, v202
	v_add_u32_e32 v247, s0, v204
	ds_read_b128 v[210:213], v244
	ds_read_b128 v[218:221], v244 offset:4096
	ds_read_b128 v[222:225], v183
	s_waitcnt lgkmcnt(3)
	v_mfma_f32_32x32x16_bf16 v[80:95], v[232:235], v[226:229], v[80:95]
	v_add_f32_e32 v214, v135, v148
	v_mov_b32_e32 v215, v214
	s_nop 1
	v_permlane32_swap_b32_e32 v214, v215
	v_mfma_f32_32x32x16_bf16 v[64:79], v[236:239], v[226:229], v[64:79]
	ds_read_b128 v[232:235], v247
	ds_read_b128 v[236:239], v247 offset:4096
	ds_read_b128 v[226:229], v182
	s_waitcnt lgkmcnt(3)
	v_mfma_f32_32x32x16_bf16 v[80:95], v[210:213], v[222:225], v[80:95]
	v_mfma_f32_32x32x16_bf16 v[64:79], v[218:221], v[222:225], v[64:79]
	v_cvt_pk_bf16_f32 v148, v175, v217
	v_cvt_pk_bf16_f32 v149, v149, v216
	v_cvt_pk_bf16_f32 v150, v150, v174
	v_cvt_pk_bf16_f32 v151, v151, v173
	v_cvt_pk_bf16_f32 v152, v154, v172
	v_cvt_pk_bf16_f32 v153, v153, v155
	s_waitcnt lgkmcnt(0)
	v_mfma_f32_32x32x16_bf16 v[80:95], v[232:235], v[226:229], v[80:95]
	v_cvt_pk_bf16_f32 v154, v145, v147
	v_permlane32_swap_b32_e32 v148, v150
	v_cvt_pk_bf16_f32 v155, v144, v146
	v_permlane32_swap_b32_e32 v152, v154
	v_cvt_pk_bf16_f32 v216, v140, v141
	v_mfma_f32_32x32x16_bf16 v[64:79], v[236:239], v[226:229], v[64:79]
	v_cvt_pk_bf16_f32 v217, v138, v139
	v_cvt_pk_bf16_f32 v218, v132, v133
	v_cvt_pk_bf16_f32 v219, v130, v131
	v_cvt_pk_bf16_f32 v220, v128, v129
	v_cvt_pk_bf16_f32 v221, v142, v143
	v_cvt_pk_bf16_f32 v222, v136, v137
	v_cvt_pk_bf16_f32 v223, v134, v135
	v_permlane32_swap_b32_e32 v149, v151
	v_permlane32_swap_b32_e32 v153, v155
	v_permlane32_swap_b32_e32 v216, v218
	v_permlane32_swap_b32_e32 v217, v219
	v_permlane32_swap_b32_e32 v220, v222
	v_permlane32_swap_b32_e32 v221, v223
	v_lshl_add_u64 v[172:173], s[64:65], 0, v[158:159]
	s_mov_b32 s0, 0x34e80000
	v_add_co_u32_e32 v132, vcc, s0, v172
	s_mov_b32 s0, 0x34ea0000
	s_nop 0
	v_addc_co_u32_e32 v133, vcc, 0, v173, vcc
	v_add_co_u32_e32 v136, vcc, s0, v172
	v_lshl_add_u64 v[174:175], s[64:65], 0, v[170:171]
	s_nop 0
	v_addc_co_u32_e32 v137, vcc, 0, v173, vcc
	global_load_dwordx4 v[128:131], v[132:133], off offset:256
	s_nop 0
	v_xor_b32_e32 v134, v243, v132
	v_mov_b32_e32 v135, v133
	s_lshl_b32 s100, s33, 4
	s_add_i32 m0, s100, 0x8000
	s_nop 0
	global_load_lds_dwordx4 v[134:135], off
	s_nop 0
	global_load_dwordx4 v[140:143], v[136:137], off offset:256
	s_nop 0
	v_xor_b32_e32 v138, v243, v136
	v_mov_b32_e32 v139, v137
	s_add_i32 m0, s100, 0xa000
	s_nop 0
	global_load_lds_dwordx4 v[138:139], off
	s_mov_b32 s0, 0x1ea04000
	v_add_co_u32_e32 v144, vcc, s0, v174
	s_nop 1
	v_addc_co_u32_e32 v145, vcc, 0, v175, vcc
	v_xor_b32_e32 v144, v242, v144
	s_add_i32 m0, s100, 0x10000
	s_nop 0
	global_load_lds_dwordx4 v[144:145], off
	ds_read_b64_tr_b16 v[224:225], v181 offset:0
	ds_read_b64_tr_b16 v[226:227], v181 offset:0x800
	ds_read_b64_tr_b16 v[228:229], v181 offset:0x1000
	ds_read_b64_tr_b16 v[230:231], v181 offset:0x1800
	ds_read_b64_tr_b16 v[232:233], v181 offset:0x2000
	ds_read_b64_tr_b16 v[234:235], v181 offset:0x2800
	ds_read_b64_tr_b16 v[236:237], v181 offset:0x3000
	ds_read_b64_tr_b16 v[238:239], v181 offset:0x3800
	s_nop 0
	s_waitcnt lgkmcnt(6)
	v_mfma_f32_32x32x16_bf16 v[0:15], v[148:151], v[224:227], v[0:15]
	ds_read_b64_tr_b16 v[224:225], v181 offset:0x200
	ds_read_b64_tr_b16 v[226:227], v181 offset:0xa00
	s_waitcnt lgkmcnt(6)
	v_mfma_f32_32x32x16_bf16 v[0:15], v[152:155], v[228:231], v[0:15]
	ds_read_b64_tr_b16 v[228:229], v181 offset:0x1200
	ds_read_b64_tr_b16 v[230:231], v181 offset:0x1a00
	s_waitcnt lgkmcnt(6)
	v_mfma_f32_32x32x16_bf16 v[0:15], v[216:219], v[232:235], v[0:15]
	ds_read_b64_tr_b16 v[232:233], v181 offset:0x2200
	ds_read_b64_tr_b16 v[234:235], v181 offset:0x2a00
	s_waitcnt lgkmcnt(6)
	v_mfma_f32_32x32x16_bf16 v[0:15], v[220:223], v[236:239], v[0:15]
	ds_read_b64_tr_b16 v[236:237], v181 offset:0x3200
	ds_read_b64_tr_b16 v[238:239], v181 offset:0x3a00
	s_waitcnt lgkmcnt(6)
	v_mfma_f32_32x32x16_bf16 v[48:63], v[148:151], v[224:227], v[48:63]
	ds_read_b64_tr_b16 v[224:225], v181 offset:0x400
	ds_read_b64_tr_b16 v[226:227], v181 offset:0xc00
	s_waitcnt lgkmcnt(6)
	v_mfma_f32_32x32x16_bf16 v[48:63], v[152:155], v[228:231], v[48:63]
	ds_read_b64_tr_b16 v[228:229], v181 offset:0x1400
	ds_read_b64_tr_b16 v[230:231], v181 offset:0x1c00
	s_waitcnt lgkmcnt(6)
	v_mfma_f32_32x32x16_bf16 v[48:63], v[216:219], v[232:235], v[48:63]
	ds_read_b64_tr_b16 v[232:233], v181 offset:0x2400
	ds_read_b64_tr_b16 v[234:235], v181 offset:0x2c00
	s_waitcnt lgkmcnt(6)
	v_mfma_f32_32x32x16_bf16 v[48:63], v[220:223], v[236:239], v[48:63]
	ds_read_b64_tr_b16 v[236:237], v181 offset:0x3400
	ds_read_b64_tr_b16 v[238:239], v181 offset:0x3c00
	s_waitcnt lgkmcnt(6)
	v_mfma_f32_32x32x16_bf16 v[32:47], v[148:151], v[224:227], v[32:47]
	ds_read_b64_tr_b16 v[224:225], v181 offset:0x600
	ds_read_b64_tr_b16 v[226:227], v181 offset:0xe00
	s_waitcnt lgkmcnt(6)
	v_mfma_f32_32x32x16_bf16 v[32:47], v[152:155], v[228:231], v[32:47]
	ds_read_b64_tr_b16 v[228:229], v181 offset:0x1600
	ds_read_b64_tr_b16 v[230:231], v181 offset:0x1e00
	s_waitcnt lgkmcnt(6)
	v_mfma_f32_32x32x16_bf16 v[32:47], v[216:219], v[232:235], v[32:47]
	ds_read_b64_tr_b16 v[232:233], v181 offset:0x2600
	ds_read_b64_tr_b16 v[234:235], v181 offset:0x2e00
	s_waitcnt lgkmcnt(6)
	v_mfma_f32_32x32x16_bf16 v[32:47], v[220:223], v[236:239], v[32:47]
	ds_read_b64_tr_b16 v[236:237], v181 offset:0x3600
	ds_read_b64_tr_b16 v[238:239], v181 offset:0x3e00
	s_waitcnt lgkmcnt(6)
	v_mfma_f32_32x32x16_bf16 v[16:31], v[148:151], v[224:227], v[16:31]
	v_max_f32_e32 v148, v81, v81
	v_max_f32_e32 v149, v80, v80
	v_max_f32_e32 v148, v149, v148
	v_max3_f32 v148, v148, v82, v83
	v_max3_f32 v148, v148, v84, v85
	v_max3_f32 v148, v148, v86, v87
	v_max3_f32 v148, v148, v88, v89
	v_max3_f32 v148, v148, v90, v91
	v_max3_f32 v148, v148, v92, v93
	s_waitcnt lgkmcnt(4)
	v_mfma_f32_32x32x16_bf16 v[16:31], v[152:155], v[228:231], v[16:31]
	v_max3_f32 v148, v148, v94, v95
	v_max3_f32 v148, v148, v64, v65
	v_max3_f32 v148, v148, v66, v67
	v_max3_f32 v148, v148, v68, v69
	v_max3_f32 v148, v148, v70, v71
	v_max3_f32 v148, v148, v72, v73
	v_max3_f32 v148, v148, v74, v75
	v_max3_f32 v148, v148, v76, v77
	s_waitcnt lgkmcnt(2)
	v_mfma_f32_32x32x16_bf16 v[16:31], v[216:219], v[232:235], v[16:31]
	v_max3_f32 v148, v148, v78, v79
	v_mov_b32_e32 v149, v148
	s_nop 1
	v_permlane32_swap_b32_e32 v148, v149
	v_max_f32_e32 v149, v149, v149
	v_max_f32_e32 v148, v148, v148
	v_max_f32_e32 v148, v148, v149
	v_sub_f32_e32 v149, v148, v209
	v_cmp_ge_f32_e32 vcc, s90, v149
	v_max_f32_e32 v149, v209, v209
	v_max_f32_e32 v148, v149, v148
	s_waitcnt lgkmcnt(0)
	v_mfma_f32_32x32x16_bf16 v[16:31], v[220:223], v[236:239], v[16:31]
	v_sub_f32_e32 v149, v209, v148
	v_mul_f32_e32 v149, 0x3dd53b94, v149
	v_exp_f32_e32 v149, v149
	s_cmp_eq_u64 vcc, exec
	s_cselect_b64 s[6:7], -1, 0
	s_barrier
	s_waitcnt vmcnt(0)
	v_cndmask_b32_e64 v152, v149, 1.0, s[6:7]
	s_waitcnt vmcnt(4)
	ds_write_b128 v185, v[128:131]
	s_waitcnt vmcnt(2)
	ds_write_b128 v186, v[140:143]
	s_waitcnt vmcnt(1)
	v_add_u32_e32 v128, 0x10000, v207
	v_cmp_gt_f32_e32 vcc, 1.0, v152
	s_waitcnt vmcnt(0)
	s_cbranch_vccz .LBB0_565
	s_and_saveexec_b64 s[0:1], s[4:5]
	ds_write_b32 v178, v152 offset:128
	s_or_b64 exec, exec, s[0:1]
	s_waitcnt lgkmcnt(0)
	v_add_u32_e32 v140, v157, v160
	ds_read_b128 v[128:131], v140 offset:224
	ds_read_b128 v[132:135], v140 offset:192
	ds_read_b128 v[136:139], v140 offset:160
	ds_read_b128 v[140:143], v140 offset:128
	s_waitcnt lgkmcnt(3)
	v_pk_mul_f32 v[12:13], v[12:13], v[128:129]
	s_waitcnt lgkmcnt(2)
	v_pk_mul_f32 v[8:9], v[8:9], v[132:133]
	s_waitcnt lgkmcnt(1)
	v_pk_mul_f32 v[4:5], v[4:5], v[136:137]
	v_pk_mul_f32 v[14:15], v[14:15], v[130:131]
	v_pk_mul_f32 v[10:11], v[10:11], v[134:135]
	v_pk_mul_f32 v[6:7], v[6:7], v[138:139]
	s_waitcnt lgkmcnt(0)
	v_pk_mul_f32 v[2:3], v[2:3], v[142:143]
	v_pk_mul_f32 v[0:1], v[0:1], v[140:141]
	v_pk_mul_f32 v[60:61], v[60:61], v[128:129]
	v_pk_mul_f32 v[56:57], v[56:57], v[132:133]
	v_pk_mul_f32 v[52:53], v[52:53], v[136:137]
	v_pk_mul_f32 v[62:63], v[62:63], v[130:131]
	v_pk_mul_f32 v[58:59], v[58:59], v[134:135]
	v_pk_mul_f32 v[54:55], v[54:55], v[138:139]
	v_pk_mul_f32 v[50:51], v[50:51], v[142:143]
	v_pk_mul_f32 v[48:49], v[48:49], v[140:141]
	v_pk_mul_f32 v[44:45], v[44:45], v[128:129]
	v_pk_mul_f32 v[40:41], v[40:41], v[132:133]
	v_pk_mul_f32 v[36:37], v[36:37], v[136:137]
	v_pk_mul_f32 v[46:47], v[46:47], v[130:131]
	v_pk_mul_f32 v[42:43], v[42:43], v[134:135]
	v_pk_mul_f32 v[38:39], v[38:39], v[138:139]
	v_pk_mul_f32 v[34:35], v[34:35], v[142:143]
	v_pk_mul_f32 v[32:33], v[32:33], v[140:141]
	v_pk_mul_f32 v[28:29], v[28:29], v[128:129]
	v_pk_mul_f32 v[24:25], v[24:25], v[132:133]
	v_pk_mul_f32 v[20:21], v[20:21], v[136:137]
	v_pk_mul_f32 v[30:31], v[30:31], v[130:131]
	v_pk_mul_f32 v[26:27], v[26:27], v[134:135]
	v_pk_mul_f32 v[22:23], v[22:23], v[138:139]
	v_pk_mul_f32 v[18:19], v[18:19], v[142:143]
	v_pk_mul_f32 v[16:17], v[16:17], v[140:141]
.LBB0_565:
	v_cndmask_b32_e64 v153, v148, v209, s[6:7]
	v_mul_f32_e32 v144, 0xbdd53b94, v153
	v_fmamk_f32 v80, v80, 0x3dd53b94, v144
	v_fmamk_f32 v81, v81, 0x3dd53b94, v144
	v_fmamk_f32 v82, v82, 0x3dd53b94, v144
	v_fmamk_f32 v83, v83, 0x3dd53b94, v144
	v_fmamk_f32 v84, v84, 0x3dd53b94, v144
	v_fmamk_f32 v85, v85, 0x3dd53b94, v144
	v_fmamk_f32 v86, v86, 0x3dd53b94, v144
	v_fmamk_f32 v87, v87, 0x3dd53b94, v144
	v_fmamk_f32 v88, v88, 0x3dd53b94, v144
	v_fmamk_f32 v89, v89, 0x3dd53b94, v144
	v_fmamk_f32 v90, v90, 0x3dd53b94, v144
	v_fmamk_f32 v91, v91, 0x3dd53b94, v144
	v_fmamk_f32 v92, v92, 0x3dd53b94, v144
	v_fmamk_f32 v93, v93, 0x3dd53b94, v144
	v_fmamk_f32 v94, v94, 0x3dd53b94, v144
	v_fmamk_f32 v95, v95, 0x3dd53b94, v144
	v_fmamk_f32 v218, v68, 0x3dd53b94, v144
	v_fmamk_f32 v148, v71, 0x3dd53b94, v144
	v_fmamk_f32 v149, v72, 0x3dd53b94, v144
	v_fmamk_f32 v219, v77, 0x3dd53b94, v144
	v_fmamk_f32 v155, v64, 0x3dd53b94, v144
	v_fmamk_f32 v209, v65, 0x3dd53b94, v144
	v_fmamk_f32 v216, v66, 0x3dd53b94, v144
	v_fmamk_f32 v217, v67, 0x3dd53b94, v144
	v_fmamk_f32 v146, v69, 0x3dd53b94, v144
	v_fmamk_f32 v147, v70, 0x3dd53b94, v144
	v_fmamk_f32 v150, v73, 0x3dd53b94, v144
	v_fmamk_f32 v151, v74, 0x3dd53b94, v144
	v_fmamk_f32 v154, v75, 0x3dd53b94, v144
	v_fmamk_f32 v145, v76, 0x3dd53b94, v144
	v_exp_f32_e32 v141, v80
	v_exp_f32_e32 v143, v81
	v_exp_f32_e32 v139, v82
	v_exp_f32_e32 v142, v83
	v_exp_f32_e32 v138, v84
	v_exp_f32_e32 v140, v85
	v_exp_f32_e32 v136, v86
	v_exp_f32_e32 v137, v87
	v_exp_f32_e32 v133, v88
	v_exp_f32_e32 v135, v89
	v_exp_f32_e32 v132, v90
	v_exp_f32_e32 v134, v91
	v_exp_f32_e32 v129, v92
	v_exp_f32_e32 v131, v93
	v_exp_f32_e32 v128, v94
	v_exp_f32_e32 v130, v95
	v_fmamk_f32 v220, v78, 0x3dd53b94, v144
	v_fmac_f32_e32 v144, 0x3dd53b94, v79
	s_waitcnt lgkmcnt(0)
	s_barrier
	ds_read_b128 v[64:67], v189 offset:32768
	ds_read_b128 v[68:71], v189 offset:40960
	ds_read_b128 v[222:225], v190 offset:32768
	ds_read_b128 v[226:229], v190 offset:40960
	v_exp_f32_e32 v155, v155
	v_exp_f32_e32 v209, v209
	s_waitcnt lgkmcnt(3)
	v_mfma_f32_32x32x16_bf16 v[80:95], v[64:67], v[120:123], 0
	v_exp_f32_e32 v216, v216
	v_exp_f32_e32 v217, v217
	s_waitcnt lgkmcnt(2)
	v_mfma_f32_32x32x16_bf16 v[64:79], v[68:71], v[120:123], 0
	v_add_f32_e32 v240, 0, v141
	v_add_f32_e32 v240, v143, v240
	s_waitcnt lgkmcnt(0)
	v_mfma_f32_32x32x16_bf16 v[64:79], v[226:229], v[124:127], v[64:79]
	v_add_f32_e32 v240, v139, v240
	v_add_f32_e32 v240, v142, v240
	v_mfma_f32_32x32x16_bf16 v[80:95], v[222:225], v[124:127], v[80:95]
	v_exp_f32_e32 v146, v146
	v_add_f32_e32 v240, v138, v240
	ds_read_b128 v[222:225], v191 offset:32768
	ds_read_b128 v[226:229], v191 offset:40960
	s_waitcnt lgkmcnt(0)
	v_mfma_f32_32x32x16_bf16 v[64:79], v[226:229], v[116:119], v[64:79]
	v_add_f32_e32 v240, v140, v240
	v_exp_f32_e32 v147, v147
	v_mfma_f32_32x32x16_bf16 v[80:95], v[222:225], v[116:119], v[80:95]
	v_add_f32_e32 v240, v136, v240
	v_add_f32_e32 v240, v137, v240
	ds_read_b128 v[222:225], v192 offset:32768
	ds_read_b128 v[226:229], v192 offset:40960
	s_waitcnt lgkmcnt(0)
	v_mfma_f32_32x32x16_bf16 v[64:79], v[226:229], v[112:115], v[64:79]
	v_exp_f32_e32 v154, v154
	v_add_f32_e32 v240, v133, v240
	v_mfma_f32_32x32x16_bf16 v[80:95], v[222:225], v[112:115], v[80:95]
	v_add_f32_e32 v240, v135, v240
	v_exp_f32_e32 v145, v145
	ds_read_b128 v[222:225], v193 offset:32768
	ds_read_b128 v[226:229], v193 offset:40960
	s_waitcnt lgkmcnt(0)
	v_mfma_f32_32x32x16_bf16 v[64:79], v[226:229], v[108:111], v[64:79]
	v_add_f32_e32 v240, v132, v240
	v_add_f32_e32 v240, v134, v240
	v_mfma_f32_32x32x16_bf16 v[80:95], v[222:225], v[108:111], v[80:95]
	v_exp_f32_e32 v144, v144
	v_add_f32_e32 v240, v129, v240
	ds_read_b128 v[222:225], v194 offset:32768
	ds_read_b128 v[226:229], v194 offset:40960
	s_waitcnt lgkmcnt(0)
	v_mfma_f32_32x32x16_bf16 v[64:79], v[226:229], v[104:107], v[64:79]
	v_add_f32_e32 v240, v131, v240
	v_exp_f32_e32 v218, v218
	v_mfma_f32_32x32x16_bf16 v[80:95], v[222:225], v[104:107], v[80:95]
	v_add_f32_e32 v240, v128, v240
	v_add_f32_e32 v240, v130, v240
	ds_read_b128 v[222:225], v195 offset:32768
	ds_read_b128 v[226:229], v195 offset:40960
	s_waitcnt lgkmcnt(0)
	v_mfma_f32_32x32x16_bf16 v[64:79], v[226:229], v[100:103], v[64:79]
	v_exp_f32_e32 v148, v148
	v_add_f32_e32 v240, v155, v240
	v_mfma_f32_32x32x16_bf16 v[80:95], v[222:225], v[100:103], v[80:95]
	v_add_f32_e32 v240, v209, v240
	v_exp_f32_e32 v149, v149
	ds_read_b128 v[222:225], v196 offset:32768
	ds_read_b128 v[226:229], v196 offset:40960
	s_waitcnt lgkmcnt(0)
	v_mfma_f32_32x32x16_bf16 v[64:79], v[226:229], v[96:99], v[64:79]
	v_add_f32_e32 v240, v216, v240
	v_add_f32_e32 v240, v217, v240
	v_mfma_f32_32x32x16_bf16 v[80:95], v[222:225], v[96:99], v[80:95]
	v_exp_f32_e32 v150, v150
	v_add_f32_e32 v240, v218, v240
	ds_read_b128 v[222:225], v199
	ds_read_b128 v[226:229], v199 offset:4096
	ds_read_b128 v[230:233], v197
	s_waitcnt lgkmcnt(0)
	v_mfma_f32_32x32x16_bf16 v[64:79], v[226:229], v[230:233], v[64:79]
	v_add_f32_e32 v240, v146, v240
	v_exp_f32_e32 v151, v151
	v_mfma_f32_32x32x16_bf16 v[80:95], v[222:225], v[230:233], v[80:95]
	v_add_f32_e32 v240, v147, v240
	v_add_f32_e32 v240, v148, v240
	ds_read_b128 v[222:225], v201
	ds_read_b128 v[226:229], v201 offset:4096
	ds_read_b128 v[230:233], v184
	s_waitcnt lgkmcnt(0)
	v_mfma_f32_32x32x16_bf16 v[64:79], v[226:229], v[230:233], v[64:79]
	v_exp_f32_e32 v219, v219
	v_add_f32_e32 v240, v149, v240
	v_mfma_f32_32x32x16_bf16 v[80:95], v[222:225], v[230:233], v[80:95]
	v_add_f32_e32 v240, v150, v240
	v_exp_f32_e32 v220, v220
	ds_read_b128 v[222:225], v203
	ds_read_b128 v[226:229], v203 offset:4096
	ds_read_b128 v[230:233], v183
	s_waitcnt lgkmcnt(0)
	v_mfma_f32_32x32x16_bf16 v[64:79], v[226:229], v[230:233], v[64:79]
	v_add_f32_e32 v240, v151, v240
	v_add_f32_e32 v240, v154, v240
	v_mfma_f32_32x32x16_bf16 v[80:95], v[222:225], v[230:233], v[80:95]
	v_add_f32_e32 v240, v145, v240
	v_add_f32_e32 v240, v219, v240
	ds_read_b128 v[222:225], v205
	ds_read_b128 v[226:229], v205 offset:4096
	ds_read_b128 v[230:233], v182
	s_waitcnt lgkmcnt(0)
	v_mfma_f32_32x32x16_bf16 v[64:79], v[226:229], v[230:233], v[64:79]
	v_add_f32_e32 v240, v220, v240
	v_add_f32_e32 v240, v144, v240
	v_mfma_f32_32x32x16_bf16 v[80:95], v[222:225], v[230:233], v[80:95]
	v_cvt_pk_bf16_f32 v226, v218, v146
	v_cvt_pk_bf16_f32 v227, v147, v148
	v_cvt_pk_bf16_f32 v228, v149, v150
	v_cvt_pk_bf16_f32 v229, v151, v154
	v_cvt_pk_bf16_f32 v230, v145, v219
	v_cvt_pk_bf16_f32 v231, v220, v144
	v_mov_b32_e32 v218, v240
	v_mov_b32_e32 v219, v240
	v_cvt_pk_bf16_f32 v148, v141, v143
	v_cvt_pk_bf16_f32 v149, v139, v142
	v_cvt_pk_bf16_f32 v150, v138, v140
	v_cvt_pk_bf16_f32 v151, v136, v137
	v_permlane32_swap_b32_e32 v218, v219
	v_permlane32_swap_b32_e32 v148, v150
	v_permlane32_swap_b32_e32 v149, v151
	v_cvt_pk_bf16_f32 v220, v133, v135
	v_cvt_pk_bf16_f32 v221, v132, v134
	v_cvt_pk_bf16_f32 v222, v129, v131
	v_cvt_pk_bf16_f32 v223, v128, v130
	v_cvt_pk_bf16_f32 v224, v155, v209
	v_cvt_pk_bf16_f32 v225, v216, v217
	s_nop 0
	v_permlane32_swap_b32_e32 v220, v222
	v_permlane32_swap_b32_e32 v221, v223
	v_permlane32_swap_b32_e32 v224, v226
	v_permlane32_swap_b32_e32 v225, v227
	v_permlane32_swap_b32_e32 v228, v230
	v_permlane32_swap_b32_e32 v229, v231
	s_mov_b32 s0, 0x34ec0000
	v_add_co_u32_e32 v132, vcc, s0, v172
	s_mov_b32 s0, 0x34ee0000
	s_nop 0
	v_addc_co_u32_e32 v133, vcc, 0, v173, vcc
	v_add_co_u32_e32 v136, vcc, s0, v172
	s_mov_b32 s0, 0x1ea06000
	s_nop 0
	v_addc_co_u32_e32 v137, vcc, 0, v173, vcc
	global_load_dwordx4 v[128:131], v[132:133], off offset:256
	s_nop 0
	v_xor_b32_e32 v134, v243, v132
	v_mov_b32_e32 v135, v133
	s_lshl_b32 s100, s33, 4
	s_add_i32 m0, s100, 0xc000
	s_nop 0
	global_load_lds_dwordx4 v[134:135], off
	s_nop 0
	global_load_dwordx4 v[140:143], v[136:137], off offset:256
	s_nop 0
	v_xor_b32_e32 v138, v243, v136
	v_mov_b32_e32 v139, v137
	s_add_i32 m0, s100, 0xe000
	s_nop 0
	global_load_lds_dwordx4 v[138:139], off
	v_add_co_u32_e32 v144, vcc, s0, v174
	s_nop 1
	v_addc_co_u32_e32 v145, vcc, 0, v175, vcc
	v_xor_b32_e32 v144, v242, v144
	s_add_i32 m0, s100, 0x12000
	s_nop 0
	global_load_lds_dwordx4 v[144:145], off
	ds_read_b64_tr_b16 v[172:173], v180 offset:0
	ds_read_b64_tr_b16 v[174:175], v180 offset:0x800
	ds_read_b64_tr_b16 v[232:233], v180 offset:0x1000
	ds_read_b64_tr_b16 v[234:235], v180 offset:0x1800
	ds_read_b64_tr_b16 v[236:237], v180 offset:0x2000
	ds_read_b64_tr_b16 v[238:239], v180 offset:0x2800
	ds_read_b64_tr_b16 v[248:249], v180 offset:0x3000
	ds_read_b64_tr_b16 v[250:251], v180 offset:0x3800
	s_nop 0
	s_waitcnt lgkmcnt(6)
	v_mfma_f32_32x32x16_bf16 v[0:15], v[148:151], v[172:175], v[0:15]
	ds_read_b64_tr_b16 v[172:173], v180 offset:0x200
	ds_read_b64_tr_b16 v[174:175], v180 offset:0xa00
	s_waitcnt lgkmcnt(6)
	v_mfma_f32_32x32x16_bf16 v[0:15], v[220:223], v[232:235], v[0:15]
	ds_read_b64_tr_b16 v[232:233], v180 offset:0x1200
	ds_read_b64_tr_b16 v[234:235], v180 offset:0x1a00
	s_waitcnt lgkmcnt(6)
	v_mfma_f32_32x32x16_bf16 v[0:15], v[224:227], v[236:239], v[0:15]
	ds_read_b64_tr_b16 v[236:237], v180 offset:0x2200
	ds_read_b64_tr_b16 v[238:239], v180 offset:0x2a00
	s_waitcnt lgkmcnt(6)
	v_mfma_f32_32x32x16_bf16 v[0:15], v[228:231], v[248:251], v[0:15]
	ds_read_b64_tr_b16 v[248:249], v180 offset:0x3200
	ds_read_b64_tr_b16 v[250:251], v180 offset:0x3a00
	s_waitcnt lgkmcnt(6)
	v_mfma_f32_32x32x16_bf16 v[48:63], v[148:151], v[172:175], v[48:63]
	ds_read_b64_tr_b16 v[172:173], v180 offset:0x400
	ds_read_b64_tr_b16 v[174:175], v180 offset:0xc00
	s_waitcnt lgkmcnt(6)
	v_mfma_f32_32x32x16_bf16 v[48:63], v[220:223], v[232:235], v[48:63]
	ds_read_b64_tr_b16 v[232:233], v180 offset:0x1400
	ds_read_b64_tr_b16 v[234:235], v180 offset:0x1c00
	s_waitcnt lgkmcnt(6)
	v_mfma_f32_32x32x16_bf16 v[48:63], v[224:227], v[236:239], v[48:63]
	ds_read_b64_tr_b16 v[236:237], v180 offset:0x2400
	ds_read_b64_tr_b16 v[238:239], v180 offset:0x2c00
	s_waitcnt lgkmcnt(6)
	v_mfma_f32_32x32x16_bf16 v[48:63], v[228:231], v[248:251], v[48:63]
	ds_read_b64_tr_b16 v[248:249], v180 offset:0x3400
	ds_read_b64_tr_b16 v[250:251], v180 offset:0x3c00
	s_waitcnt lgkmcnt(6)
	v_mfma_f32_32x32x16_bf16 v[32:47], v[148:151], v[172:175], v[32:47]
	ds_read_b64_tr_b16 v[172:173], v180 offset:0x600
	ds_read_b64_tr_b16 v[174:175], v180 offset:0xe00
	s_waitcnt lgkmcnt(6)
	v_mfma_f32_32x32x16_bf16 v[32:47], v[220:223], v[232:235], v[32:47]
	ds_read_b64_tr_b16 v[232:233], v180 offset:0x1600
	ds_read_b64_tr_b16 v[234:235], v180 offset:0x1e00
	s_waitcnt lgkmcnt(6)
	v_mfma_f32_32x32x16_bf16 v[32:47], v[224:227], v[236:239], v[32:47]
	ds_read_b64_tr_b16 v[236:237], v180 offset:0x2600
	ds_read_b64_tr_b16 v[238:239], v180 offset:0x2e00
	s_waitcnt lgkmcnt(6)
	v_mfma_f32_32x32x16_bf16 v[32:47], v[228:231], v[248:251], v[32:47]
	ds_read_b64_tr_b16 v[248:249], v180 offset:0x3600
	ds_read_b64_tr_b16 v[250:251], v180 offset:0x3e00
	s_waitcnt lgkmcnt(6)
	v_mfma_f32_32x32x16_bf16 v[16:31], v[148:151], v[172:175], v[16:31]
	v_max_f32_e32 v148, v81, v81
	v_max_f32_e32 v149, v80, v80
	v_max_f32_e32 v148, v149, v148
	v_max3_f32 v148, v148, v82, v83
	v_max3_f32 v148, v148, v84, v85
	v_max3_f32 v148, v148, v86, v87
	v_max3_f32 v148, v148, v88, v89
	v_max3_f32 v148, v148, v90, v91
	v_max3_f32 v148, v148, v92, v93
	s_waitcnt lgkmcnt(4)
	v_mfma_f32_32x32x16_bf16 v[16:31], v[220:223], v[232:235], v[16:31]
	v_max3_f32 v148, v148, v94, v95
	v_max3_f32 v148, v148, v64, v65
	v_max3_f32 v148, v148, v66, v67
	v_max3_f32 v148, v148, v68, v69
	v_max3_f32 v148, v148, v70, v71
	v_max3_f32 v148, v148, v72, v73
	v_max3_f32 v148, v148, v74, v75
	v_max3_f32 v148, v148, v76, v77
	s_waitcnt lgkmcnt(2)
	v_mfma_f32_32x32x16_bf16 v[16:31], v[224:227], v[236:239], v[16:31]
	v_max3_f32 v148, v148, v78, v79
	v_mov_b32_e32 v149, v148
	s_nop 1
	v_permlane32_swap_b32_e32 v148, v149
	v_max_f32_e32 v149, v149, v149
	v_max_f32_e32 v148, v148, v148
	v_max_f32_e32 v148, v148, v149
	v_sub_f32_e32 v149, v148, v153
	v_cmp_ge_f32_e32 vcc, s90, v149
	v_max_f32_e32 v149, v153, v153
	v_max_f32_e32 v149, v149, v148
	s_waitcnt lgkmcnt(0)
	v_mfma_f32_32x32x16_bf16 v[16:31], v[228:231], v[248:251], v[16:31]
	v_sub_f32_e32 v148, v153, v149
	v_mul_f32_e32 v148, 0x3dd53b94, v148
	v_exp_f32_e32 v148, v148
	s_cmp_eq_u64 vcc, exec
	s_cselect_b64 s[6:7], -1, 0
	s_barrier
	s_waitcnt vmcnt(0)
	v_cndmask_b32_e64 v148, v148, 1.0, s[6:7]
	v_cmp_gt_f32_e32 vcc, 1.0, v148
	s_waitcnt vmcnt(4)
	ds_write_b128 v185, v[128:131] offset:16384
	s_waitcnt vmcnt(2)
	ds_write_b128 v186, v[140:143] offset:16384
	s_waitcnt vmcnt(1)
	s_waitcnt vmcnt(0)
	s_cbranch_vccz .LBB0_569
	s_and_saveexec_b64 s[0:1], s[4:5]
	ds_write_b32 v178, v148 offset:128
	s_or_b64 exec, exec, s[0:1]
	s_waitcnt lgkmcnt(0)
	v_add_u32_e32 v140, v157, v160
	ds_read_b128 v[128:131], v140 offset:224
	ds_read_b128 v[132:135], v140 offset:192
	ds_read_b128 v[136:139], v140 offset:160
	ds_read_b128 v[140:143], v140 offset:128
	s_waitcnt lgkmcnt(3)
	v_pk_mul_f32 v[12:13], v[12:13], v[128:129]
	s_waitcnt lgkmcnt(2)
	v_pk_mul_f32 v[8:9], v[8:9], v[132:133]
	s_waitcnt lgkmcnt(1)
	v_pk_mul_f32 v[4:5], v[4:5], v[136:137]
	v_pk_mul_f32 v[14:15], v[14:15], v[130:131]
	v_pk_mul_f32 v[10:11], v[10:11], v[134:135]
	v_pk_mul_f32 v[6:7], v[6:7], v[138:139]
	s_waitcnt lgkmcnt(0)
	v_pk_mul_f32 v[2:3], v[2:3], v[142:143]
	v_pk_mul_f32 v[0:1], v[0:1], v[140:141]
	v_pk_mul_f32 v[60:61], v[60:61], v[128:129]
	v_pk_mul_f32 v[56:57], v[56:57], v[132:133]
	v_pk_mul_f32 v[52:53], v[52:53], v[136:137]
	v_pk_mul_f32 v[62:63], v[62:63], v[130:131]
	v_pk_mul_f32 v[58:59], v[58:59], v[134:135]
	v_pk_mul_f32 v[54:55], v[54:55], v[138:139]
	v_pk_mul_f32 v[50:51], v[50:51], v[142:143]
	v_pk_mul_f32 v[48:49], v[48:49], v[140:141]
	v_pk_mul_f32 v[44:45], v[44:45], v[128:129]
	v_pk_mul_f32 v[40:41], v[40:41], v[132:133]
	v_pk_mul_f32 v[36:37], v[36:37], v[136:137]
	v_pk_mul_f32 v[46:47], v[46:47], v[130:131]
	v_pk_mul_f32 v[42:43], v[42:43], v[134:135]
	v_pk_mul_f32 v[38:39], v[38:39], v[138:139]
	v_pk_mul_f32 v[34:35], v[34:35], v[142:143]
	v_pk_mul_f32 v[32:33], v[32:33], v[140:141]
	v_pk_mul_f32 v[28:29], v[28:29], v[128:129]
	v_pk_mul_f32 v[24:25], v[24:25], v[132:133]
	v_pk_mul_f32 v[20:21], v[20:21], v[136:137]
	v_pk_mul_f32 v[30:31], v[30:31], v[130:131]
	v_pk_mul_f32 v[26:27], v[26:27], v[134:135]
	v_pk_mul_f32 v[22:23], v[22:23], v[138:139]
	v_pk_mul_f32 v[18:19], v[18:19], v[142:143]
	v_pk_mul_f32 v[16:17], v[16:17], v[140:141]
